# plus: batched LDS fragment reads before MFMAs in spatial-gating unit k-steps and compressed-branch PV
# baseline (speedup 1.0000x reference)
; __device__ __forceinline__ void attn_unit(int bg, int pb, bool build, const bf16* Q, const bf16* KV, const bf16* KCN, const bf16* VCT, const float* GATES, const float* rel_bias, bf16* A, unsigned char* lds) {
;     ...
;         mx = fmaxf(mx, __shfl_xor(mx, 16)); mx = fmaxf(mx, __shfl_xor(mx, 32));
;         float sum = 0.f;
; #pragma unroll
;         for (int st = 0; st < 4; ++st)
; #pragma unroll
;             for (int ph = 0; ph < 2; ++ph)
; #pragma unroll
;                 for (int j = 0; j < 4; ++j) { const float p = pc[st][ph][j] > -1e29f ? __builtin_amdgcn_exp2f(pc[st][ph][j] - mx) : 0.f; pc[st][ph][j] = p; sum += p; }
;         sum += __shfl_xor(sum, 16); sum += __shfl_xor(sum, 32);
.Lcmp_done:
.LBB0_322:
	v_and_b32_e32 v3, 64, v226
	v_xor_b32_e32 v2, 16, v226
	v_add_u32_e32 v3, 64, v3
	v_cmp_lt_i32_e32 vcc, v2, v3
	v_xor_b32_e32 v5, 32, v226
	v_max_f32_e32 v4, v8, v8
	v_cndmask_b32_e32 v2, v226, v2, vcc
	v_lshlrev_b32_e32 v136, 2, v2
	ds_bpermute_b32 v2, v136, v8
	v_cmp_lt_i32_e32 vcc, v5, v3
	s_lshl_b32 s10, s12, 5
	s_add_i32 s10, s10, s75
	v_cndmask_b32_e32 v3, v226, v5, vcc
	s_waitcnt lgkmcnt(0)
	v_max_f32_e32 v2, v2, v2
	v_max_f32_e32 v2, v4, v2
	v_lshlrev_b32_e32 v137, 2, v3
	ds_bpermute_b32 v3, v137, v2
	v_cmp_lt_f32_e32 vcc, s95, v6
	v_lshlrev_b32_e32 v138, 2, v59
	s_waitcnt lgkmcnt(0)
	v_max_f32_e32 v3, v3, v3
	v_max_f32_e32 v8, v2, v3
	v_sub_f32_e32 v2, v15, v8
	v_exp_f32_e32 v52, v2
	v_sub_f32_e32 v2, v26, v8
	v_exp_f32_e32 v62, v2
	v_sub_f32_e32 v2, v27, v8
	v_exp_f32_e32 v63, v2
	v_sub_f32_e32 v2, v28, v8
	v_exp_f32_e32 v64, v2
	v_sub_f32_e32 v2, v29, v8
	v_exp_f32_e32 v65, v2
	v_sub_f32_e32 v2, v30, v8
	v_exp_f32_e32 v66, v2
	v_sub_f32_e32 v2, v31, v8
	v_exp_f32_e32 v67, v2
	v_sub_f32_e32 v2, v33, v8
	v_exp_f32_e32 v56, v2
	v_sub_f32_e32 v2, v32, v8
	v_exp_f32_e32 v57, v2
	v_sub_f32_e32 v2, v34, v8
	v_exp_f32_e32 v54, v2
	v_sub_f32_e32 v2, v35, v8
	v_exp_f32_e32 v55, v2
	v_sub_f32_e32 v2, v36, v8
	v_exp_f32_e32 v68, v2
	v_sub_f32_e32 v2, v37, v8
	v_exp_f32_e32 v69, v2
	v_sub_f32_e32 v2, v38, v8
	v_exp_f32_e32 v70, v2
	v_sub_f32_e32 v2, v39, v8
	v_sub_f32_e32 v3, v14, v8
	v_exp_f32_e32 v71, v2
	v_sub_f32_e32 v2, v6, v8
	v_exp_f32_e32 v53, v3
	v_exp_f32_e32 v2, v2
	v_sub_f32_e32 v3, v7, v8
	v_exp_f32_e32 v3, v3
	v_sub_f32_e32 v5, v47, v8
	v_cndmask_b32_e32 v11, 0, v2, vcc
	v_cmp_lt_f32_e32 vcc, s95, v7
	v_sub_f32_e32 v2, v12, v8
	v_exp_f32_e32 v2, v2
	v_cndmask_b32_e32 v10, 0, v3, vcc
	v_sub_f32_e32 v3, v16, v8
	v_exp_f32_e32 v3, v3
	v_cmp_lt_f32_e32 vcc, s95, v12
	v_exp_f32_e32 v6, v5
	v_sub_f32_e32 v7, v49, v8
	v_cndmask_b32_e32 v13, 0, v2, vcc
	v_cmp_lt_f32_e32 vcc, s95, v16
	v_sub_f32_e32 v2, v17, v8
	v_exp_f32_e32 v2, v2
	v_cndmask_b32_e32 v12, 0, v3, vcc
	v_sub_f32_e32 v3, v40, v8
	v_exp_f32_e32 v3, v3
	v_cmp_lt_f32_e32 vcc, s95, v17
	v_exp_f32_e32 v9, v7
	s_nop 0
	v_cndmask_b32_e32 v17, 0, v2, vcc
	v_cmp_lt_f32_e32 vcc, s95, v40
	v_sub_f32_e32 v2, v41, v8
	v_exp_f32_e32 v2, v2
	v_cndmask_b32_e32 v16, 0, v3, vcc
	v_sub_f32_e32 v3, v42, v8
	v_exp_f32_e32 v3, v3
	v_cmp_lt_f32_e32 vcc, s95, v41
	s_nop 1
	v_cndmask_b32_e32 v43, 0, v2, vcc
	v_cmp_lt_f32_e32 vcc, s95, v42
	v_sub_f32_e32 v2, v44, v8
	v_exp_f32_e32 v2, v2
	v_cndmask_b32_e32 v42, 0, v3, vcc
	v_sub_f32_e32 v3, v45, v8
	v_exp_f32_e32 v4, v3
	v_cmp_lt_f32_e32 vcc, s95, v44
	s_nop 1
	v_cndmask_b32_e32 v3, 0, v2, vcc
	v_cmp_lt_f32_e32 vcc, s95, v45
	s_nop 1
	v_cndmask_b32_e32 v2, 0, v4, vcc
	v_sub_f32_e32 v4, v46, v8
	v_exp_f32_e32 v4, v4
	v_cmp_lt_f32_e32 vcc, s95, v46
	s_nop 1
	v_cndmask_b32_e32 v5, 0, v4, vcc
	v_cmp_lt_f32_e32 vcc, s95, v47
	s_nop 1
	v_cndmask_b32_e32 v4, 0, v6, vcc
	v_sub_f32_e32 v6, v48, v8
	v_exp_f32_e32 v6, v6
	v_cmp_lt_f32_e32 vcc, s95, v48
	s_nop 1
	v_cndmask_b32_e32 v7, 0, v6, vcc
	v_cmp_lt_f32_e32 vcc, s95, v49
	s_nop 1
	v_cndmask_b32_e32 v6, 0, v9, vcc
	v_sub_f32_e32 v9, v50, v8
	v_exp_f32_e32 v9, v9
	v_sub_f32_e32 v8, v51, v8
	v_exp_f32_e32 v8, v8
	v_cmp_lt_f32_e32 vcc, s95, v50
	s_nop 1
	v_cndmask_b32_e32 v9, 0, v9, vcc
	v_cmp_lt_f32_e32 vcc, s95, v51
	s_nop 1
	v_cndmask_b32_e32 v8, 0, v8, vcc
	v_cmp_lt_f32_e32 vcc, s95, v39
	s_nop 1
	v_cndmask_b32_e32 v51, 0, v71, vcc
	v_cmp_lt_f32_e32 vcc, s95, v38
	s_nop 1
	v_cndmask_b32_e32 v50, 0, v70, vcc
	v_cmp_lt_f32_e32 vcc, s95, v37
	s_nop 1
	v_cndmask_b32_e32 v49, 0, v69, vcc
	v_cmp_lt_f32_e32 vcc, s95, v36
	s_nop 1
	v_cndmask_b32_e32 v48, 0, v68, vcc
	v_cmp_lt_f32_e32 vcc, s95, v35
	s_nop 1
	v_cndmask_b32_e32 v55, 0, v55, vcc
	v_cmp_lt_f32_e32 vcc, s95, v34
	v_or_b32_e32 v34, s10, v58
	v_readlane_b32 s10, v254, 50
	v_cndmask_b32_e32 v54, 0, v54, vcc
	v_cmp_lt_f32_e32 vcc, s95, v32
	v_lshl_or_b32 v34, v34, 7, v138
	v_add_u32_e32 v38, 0, v34
	v_cndmask_b32_e32 v57, 0, v57, vcc
	v_cmp_lt_f32_e32 vcc, s95, v33
	s_nop 1
	v_cndmask_b32_e32 v56, 0, v56, vcc
	v_cmp_lt_f32_e32 vcc, s95, v31
	s_nop 1
	v_cndmask_b32_e32 v31, 0, v67, vcc
	v_cmp_lt_f32_e32 vcc, s95, v30
	s_nop 1
	v_cndmask_b32_e32 v30, 0, v66, vcc
	v_cmp_lt_f32_e32 vcc, s95, v29
	s_nop 1
	v_cndmask_b32_e32 v29, 0, v65, vcc
	v_cmp_lt_f32_e32 vcc, s95, v28
	s_nop 1
	v_cndmask_b32_e32 v28, 0, v64, vcc
	v_cmp_lt_f32_e32 vcc, s95, v27
	s_nop 1
	v_cndmask_b32_e32 v27, 0, v63, vcc
	v_cmp_lt_f32_e32 vcc, s95, v26
	s_nop 1
	v_cndmask_b32_e32 v26, 0, v62, vcc
	v_cmp_lt_f32_e32 vcc, s95, v15
	s_nop 1
	v_cndmask_b32_e32 v32, 0, v52, vcc
	v_cmp_lt_f32_e32 vcc, s95, v14
	v_add_f32_e32 v33, 0, v32
	v_add_u32_e32 v52, 0x800, v38
	v_cndmask_b32_e32 v15, 0, v53, vcc
	v_add_f32_e32 v14, v15, v33
	v_add_f32_e32 v14, v26, v14
	v_add_f32_e32 v14, v27, v14
	v_add_f32_e32 v14, v28, v14
	v_add_f32_e32 v14, v29, v14
	v_add_f32_e32 v14, v30, v14
	v_add_f32_e32 v14, v31, v14
	v_add_f32_e32 v14, v56, v14
	v_add_f32_e32 v14, v57, v14
	v_add_f32_e32 v14, v54, v14
	v_add_f32_e32 v14, v55, v14
	v_add_f32_e32 v14, v48, v14
	v_add_f32_e32 v14, v49, v14
	v_add_f32_e32 v14, v50, v14
	v_add_f32_e32 v14, v51, v14
	v_add_f32_e32 v14, v10, v14
	v_add_f32_e32 v14, v11, v14
	v_add_f32_e32 v14, v12, v14
	v_add_f32_e32 v14, v13, v14
	v_add_f32_e32 v14, v16, v14
	v_add_f32_e32 v14, v17, v14
	v_add_f32_e32 v14, v42, v14
	v_add_f32_e32 v14, v43, v14
	v_add_f32_e32 v14, v2, v14
	v_add_f32_e32 v14, v3, v14
	v_add_f32_e32 v14, v4, v14
	v_add_f32_e32 v14, v5, v14
	v_add_f32_e32 v14, v6, v14
	v_add_f32_e32 v14, v7, v14
	v_add_f32_e32 v14, v8, v14
	v_add_f32_e32 v14, v9, v14
	ds_bpermute_b32 v33, v136, v14
	v_add_u32_e32 v53, s10, v0
	s_waitcnt lgkmcnt(0)
; __device__ __forceinline__ bf16x8 pack_p(const float* a, const float* b) { u32x4 w; w.x = cvtpk(a[0], a[1]); w.y = cvtpk(a[2], a[3]); w.z = cvtpk(b[0], b[1]); w.w = cvtpk(b[2], b[3]); return __builtin_bit_cast(bf16x8, w); }
; __device__ __forceinline__ bf16x8 ldv(const bf16* p) { const s16x4 lo = *(const s16x4*)p, hi = *(const s16x4*)(p + 16); return __builtin_shufflevector(lo, hi, 0, 1, 2, 3, 4, 5, 6, 7); }
; __device__ __forceinline__ void attn_unit(int bg, int pb, bool build, const bf16* Q, const bf16* KV, const bf16* KCN, const bf16* VCT, const float* GATES, const float* rel_bias, bf16* A, unsigned char* lds) {
;     ...
;         sum += __shfl_xor(sum, 16); sum += __shfl_xor(sum, 32);
;         const float inv = sum > 0.f ? 1.f / sum : 0.f;
;         f32x4 oc[4];
; #pragma unroll
;         for (int dt = 0; dt < 4; ++dt) oc[dt] = (f32x4){0.f, 0.f, 0.f, 0.f};
;         const int prow = (hl * 32 + half * 16 + qi) * 32;
; #pragma unroll
;         for (int st = 0; st < 4; ++st) {
; #pragma unroll
;             for (int ph = 0; ph < 2; ++ph) {
; #pragma unroll
;                 for (int j = 0; j < 4; ++j) pc[st][ph][j] *= inv;
;                 const int jj = st * 8 + ph * 4 + q4;
;                 impA[prow + jj] = pc[st][ph][0] + pc[st][ph][1] + pc[st][ph][2] + 0.5f * pc[st][ph][3];
;                 impB[prow + jj] = 0.5f * pc[st][ph][3];
;             }
;             if (st < nst) {
;                 const bf16x8 pf = pack_p(pc[st][0], pc[st][1]);
; #pragma unroll
;                 for (int dt = 0; dt < 4; ++dt) { const bf16x8 vf = ldv((const bf16*)(lds + AL_CV + (dt * 16 + qi) * CVP) + st * 32 + q4 * 4); oc[dt] = __builtin_amdgcn_mfma_f32_16x16x32_bf16(vf, pf, oc[dt], 0, 0, 0); }
;             }
;         }
; #pragma unroll
;         for (int dt = 0; dt < 4; ++dt) acc[dt] = oc[dt] * g0;
	v_add_f32_e32 v14, v14, v33
	ds_bpermute_b32 v33, v137, v14
	s_waitcnt lgkmcnt(0)
	v_add_f32_e32 v0, v14, v33
	v_div_scale_f32 v14, s[10:11], v0, v0, 1.0
	v_rcp_f32_e32 v33, v14
	s_movk_i32 s10, 0x110
	v_mad_u32_u24 v44, v58, s10, v53
	v_fma_f32 v34, -v14, v33, 1.0
	v_fmac_f32_e32 v33, v34, v33
	v_div_scale_f32 v34, vcc, 1.0, v0, 1.0
	v_mul_f32_e32 v35, v34, v33
	v_fma_f32 v36, -v14, v35, v34
	v_fmac_f32_e32 v35, v36, v33
	v_fma_f32 v14, -v14, v35, v34
	v_div_fmas_f32 v14, v14, v33, v35
	v_div_fixup_f32 v14, v14, v0, 1.0
	v_cmp_lt_f32_e32 vcc, 0, v0
	s_nop 1
	v_cndmask_b32_e32 v14, 0, v14, vcc
	v_mov_b32_e32 v33, v14
	v_pk_mul_f32 v[34:35], v[26:27], v[14:15] op_sel_hi:[1,0]
	v_pk_mul_f32 v[32:33], v[14:15], v[32:33]
	v_mul_f32_e32 v15, 0.5, v35
	v_pk_mul_f32 v[36:37], v[28:29], v[14:15] op_sel_hi:[1,0]
	v_add_f32_e32 v0, v32, v33
	v_pk_mul_f32 v[30:31], v[30:31], v[14:15] op_sel_hi:[1,0]
	v_add_f32_e32 v26, v36, v37
	v_add_f32_e32 v0, v34, v0
	v_add_f32_e32 v26, v30, v26
	v_fmac_f32_e32 v0, 0.5, v35
	v_fmac_f32_e32 v26, 0.5, v31
	v_mul_f32_e32 v27, 0.5, v31
	ds_write2_b32 v52, v0, v26 offset1:4
	v_add_u32_e32 v0, 0x4800, v38
	ds_write2_b32 v0, v15, v27 offset1:4
	v_add_u32_e32 v15, 0x1000, v44
	v_cvt_pk_bf16_f32 v38, v32, v33
	v_cvt_pk_bf16_f32 v41, v30, v31
	ds_read2_b64 v[30:33], v15 offset0:32 offset1:36
	v_add_u32_e32 v15, 0x2000, v44
	v_cvt_pk_bf16_f32 v39, v34, v35
	v_cvt_pk_bf16_f32 v40, v36, v37
	ds_read2_b64 v[34:37], v15 offset0:64 offset1:68
	v_add_u32_e32 v15, 0x3000, v44
	ds_read2_b64 v[26:29], v44 offset1:4
	ds_read2_b64 v[44:47], v15 offset0:96 offset1:100
	v_mul_u32_u24_e32 v15, 0x110, v58
	s_waitcnt lgkmcnt(1)
	v_mfma_f32_16x16x32_bf16 v[26:29], v[26:29], v[38:41], 0
	v_mul_f32_e64 v48, v48, v14
	v_mul_f32_e64 v49, v49, v14
	v_pk_mul_f32 v[50:51], v[50:51], v[14:15] op_sel_hi:[1,0]
	s_andn2_b64 vcc, exec, s[86:87]
	v_mfma_f32_16x16x32_bf16 v[30:33], v[30:33], v[38:41], 0
	v_mfma_f32_16x16x32_bf16 v[34:37], v[34:37], v[38:41], 0
	s_waitcnt lgkmcnt(0)
	v_mfma_f32_16x16x32_bf16 v[38:41], v[44:47], v[38:41], 0
	v_mul_f32_e64 v44, v56, v14
	v_mul_f32_e64 v45, v57, v14
	v_pk_mul_f32 v[46:47], v[54:55], v[14:15] op_sel_hi:[1,0]
	v_add_f32_e32 v54, v44, v45
	v_add_f32_e32 v56, v48, v49
	v_add_f32_e32 v54, v46, v54
	v_add_f32_e32 v56, v50, v56
	v_fmac_f32_e32 v54, 0.5, v47
	v_fmac_f32_e32 v56, 0.5, v51
	v_mul_f32_e32 v55, 0.5, v47
	v_mul_f32_e32 v57, 0.5, v51
	ds_write2_b32 v52, v54, v56 offset0:8 offset1:12
	ds_write2_b32 v0, v55, v57 offset0:8 offset1:12
	v_add_u32_e32 v56, v53, v15
	v_add_u32_e32 v55, 0x1000, v56
	v_add_u32_e32 v54, 0x2000, v56
	v_add_u32_e32 v53, 0x3000, v56
	s_cbranch_vccnz .LBB0_324
	v_cvt_pk_bf16_f32 v44, v44, v45
	v_cvt_pk_bf16_f32 v45, v46, v47
	v_cvt_pk_bf16_f32 v46, v48, v49
	v_cvt_pk_bf16_f32 v47, v50, v51
	ds_read2_b64 v[180:183], v56 offset0:8 offset1:12
	ds_read2_b64 v[184:187], v55 offset0:40 offset1:44
	ds_read2_b64 v[188:191], v54 offset0:72 offset1:76
	ds_read2_b64 v[192:195], v53 offset0:104 offset1:108
	s_waitcnt lgkmcnt(3)
	v_mfma_f32_16x16x32_bf16 v[26:29], v[180:183], v[44:47], v[26:29]
	s_waitcnt lgkmcnt(2)
	v_mfma_f32_16x16x32_bf16 v[30:33], v[184:187], v[44:47], v[30:33]
	s_waitcnt lgkmcnt(1)
	v_mfma_f32_16x16x32_bf16 v[34:37], v[188:191], v[44:47], v[34:37]
	s_waitcnt lgkmcnt(0)
	v_mfma_f32_16x16x32_bf16 v[38:41], v[192:195], v[44:47], v[38:41]
.LBB0_324:
	v_mov_b32_e32 v15, v14
	v_pk_mul_f32 v[10:11], v[10:11], v[14:15]
	v_pk_mul_f32 v[16:17], v[16:17], v[14:15]
	v_pk_mul_f32 v[12:13], v[12:13], v[14:15]
	v_add_f32_e32 v44, v10, v11
	v_pk_mul_f32 v[42:43], v[42:43], v[14:15]
	v_add_f32_e32 v46, v16, v17
	v_add_f32_e32 v44, v12, v44
	v_add_f32_e32 v46, v42, v46
	v_mul_f32_e32 v45, 0.5, v13
	v_fmac_f32_e32 v44, 0.5, v13
	v_mul_f32_e32 v47, 0.5, v43
	v_fmac_f32_e32 v46, 0.5, v43
	s_andn2_b64 vcc, exec, s[0:1]
	ds_write2_b32 v52, v44, v46 offset0:16 offset1:20
	ds_write2_b32 v0, v45, v47 offset0:16 offset1:20
	s_cbranch_vccnz .LBB0_326
	v_cvt_pk_bf16_f32 v10, v10, v11
	v_cvt_pk_bf16_f32 v11, v12, v13
	v_cvt_pk_bf16_f32 v13, v42, v43
	v_cvt_pk_bf16_f32 v12, v16, v17
	ds_read2_b64 v[180:183], v56 offset0:16 offset1:20
	ds_read2_b64 v[184:187], v55 offset0:48 offset1:52
	ds_read2_b64 v[188:191], v54 offset0:80 offset1:84
	ds_read2_b64 v[192:195], v53 offset0:112 offset1:116
	s_waitcnt lgkmcnt(3)
	v_mfma_f32_16x16x32_bf16 v[26:29], v[180:183], v[10:13], v[26:29]
	s_waitcnt lgkmcnt(2)
	v_mfma_f32_16x16x32_bf16 v[30:33], v[184:187], v[10:13], v[30:33]
	s_waitcnt lgkmcnt(1)
	v_mfma_f32_16x16x32_bf16 v[34:37], v[188:191], v[10:13], v[34:37]
	s_waitcnt lgkmcnt(0)
	v_mfma_f32_16x16x32_bf16 v[38:41], v[192:195], v[10:13], v[38:41]
.LBB0_326:
	v_pk_mul_f32 v[2:3], v[2:3], v[14:15]
	v_pk_mul_f32 v[6:7], v[6:7], v[14:15]
	v_pk_mul_f32 v[4:5], v[4:5], v[14:15]
	v_add_f32_e32 v10, v2, v3
	v_pk_mul_f32 v[8:9], v[8:9], v[14:15]
	v_add_f32_e32 v12, v6, v7
	v_add_f32_e32 v10, v4, v10
	v_add_f32_e32 v12, v8, v12
	v_mul_f32_e32 v11, 0.5, v5
	v_fmac_f32_e32 v10, 0.5, v5
	v_mul_f32_e32 v13, 0.5, v9
	v_fmac_f32_e32 v12, 0.5, v9
	s_andn2_b64 vcc, exec, s[6:7]
	ds_write2_b32 v52, v10, v12 offset0:24 offset1:28
	ds_write2_b32 v0, v11, v13 offset0:24 offset1:28
	s_cbranch_vccnz .LBB0_328
	v_cvt_pk_bf16_f32 v2, v2, v3
	v_cvt_pk_bf16_f32 v3, v4, v5
	v_cvt_pk_bf16_f32 v4, v6, v7
	v_cvt_pk_bf16_f32 v5, v8, v9
	ds_read2_b64 v[180:183], v56 offset0:24 offset1:28
	ds_read2_b64 v[184:187], v55 offset0:56 offset1:60
	ds_read2_b64 v[188:191], v54 offset0:88 offset1:92
	ds_read2_b64 v[192:195], v53 offset0:120 offset1:124
	s_waitcnt lgkmcnt(3)
	v_mfma_f32_16x16x32_bf16 v[26:29], v[180:183], v[2:5], v[26:29]
	s_waitcnt lgkmcnt(2)
	v_mfma_f32_16x16x32_bf16 v[30:33], v[184:187], v[2:5], v[30:33]
	s_waitcnt lgkmcnt(1)
	v_mfma_f32_16x16x32_bf16 v[34:37], v[188:191], v[2:5], v[34:37]
	s_waitcnt lgkmcnt(0)
	v_mfma_f32_16x16x32_bf16 v[38:41], v[192:195], v[2:5], v[38:41]

; __device__ __forceinline__ void cs_pair(int cu, int su0, int su1, const bf16* KVB, const bf16* w1k, const bf16* w1v, const bf16* w2k, const bf16* w2v, const float* bias1, const float* kn0, bf16* KCN, bf16* VCT, ...
;     ...
; #pragma unroll
;             for (int th = 0; th < 2; ++th) {
;                 const int tt = 2 * wl + th, nks = (16 * tt + 15) / 32 + 1, t = tt * 16 + qi;
;                 const bf16* wp = WS + ((size_t)g * 128 + t) * 128 + q4 * 8;
;                 bf16x8 bw[4];
; #pragma unroll
;                 for (int ks = 0; ks < 4; ++ks) bw[ks] = (ks < nks) ? *(const bf16x8*)(wp + ks * 32) : (bf16x8){0, 0, 0, 0, 0, 0, 0, 0};
;                 u32x2 uv[8];
; #pragma unroll
;                 for (int dt = 0; dt < 8; ++dt) uv[dt] = *(const u32x2*)(U + (size_t)(r0 + t) * 1024 + g * 128 + dt * 16 + q4 * 4);
;                 const float bias = bs[g * 128 + t];
;                 f32x4 acc[8];
; #pragma unroll
;                 for (int dt = 0; dt < 8; ++dt) acc[dt] = (f32x4){0.f, 0.f, 0.f, 0.f};
; #pragma unroll
;                 for (int ks = 0; ks < 4; ++ks) if (ks < nks) {
; #pragma unroll
;                     for (int dt = 0; dt < 8; ++dt) { const bf16x8 av = *(const bf16x8*)(vnT + (dt * 16 + qi) * 136 + (((ks * 4 + q4) ^ (dt * 2 + (qi >> 3))) << 3)); acc[dt] = __builtin_amdgcn_mfma_f32_16x16x32_bf16(av, bw[ks], acc[dt], 0, 0, 0); }
;                 }
.LBB0_719:
	v_add_u32_e32 v2, s64, v130
	v_ashrrev_i32_e32 v3, 31, v2
	v_lshl_add_u64 v[92:93], v[88:89], 0, s[38:39]
	v_lshlrev_b64 v[110:111], 11, v[2:3]
	v_lshl_add_u64 v[2:3], v[92:93], 0, v[110:111]
	global_load_dwordx2 v[108:109], v[2:3], off
	global_load_dwordx2 v[106:107], v[2:3], off offset:32
	global_load_dwordx2 v[104:105], v[2:3], off offset:64
	global_load_dwordx2 v[102:103], v[2:3], off offset:96
	global_load_dwordx2 v[100:101], v[2:3], off offset:128
	global_load_dwordx2 v[98:99], v[2:3], off offset:160
	global_load_dwordx2 v[96:97], v[2:3], off offset:192
	global_load_dwordx2 v[94:95], v[2:3], off offset:224
	v_lshl_add_u64 v[2:3], v[0:1], 2, s[14:15]
	global_load_dword v0, v[2:3], off
	ds_read_b128 v[22:25], v140 offset:10240
	ds_read_b128 v[26:29], v141 offset:14592
	ds_read_b128 v[30:33], v142 offset:18944
	ds_read_b128 v[18:21], v143 offset:23296
	ds_read_b128 v[14:17], v144 offset:27648
	ds_read_b128 v[10:13], v145 offset:32000
	ds_read_b128 v[2:5], v146 offset:36352
	ds_read_b128 v[6:9], v147 offset:40704
	s_waitcnt vmcnt(9) lgkmcnt(7)
	v_mfma_f32_16x16x32_bf16 v[62:65], v[22:25], v[34:37], 0
	s_andn2_b64 vcc, exec, s[16:17]
	s_waitcnt lgkmcnt(6)
	v_mfma_f32_16x16x32_bf16 v[58:61], v[26:29], v[34:37], 0
	s_waitcnt lgkmcnt(5)
	v_mfma_f32_16x16x32_bf16 v[54:57], v[30:33], v[34:37], 0
	s_waitcnt lgkmcnt(4)
	v_mfma_f32_16x16x32_bf16 v[50:53], v[18:21], v[34:37], 0
	s_waitcnt lgkmcnt(3)
	v_mfma_f32_16x16x32_bf16 v[46:49], v[14:17], v[34:37], 0
	s_waitcnt lgkmcnt(2)
	v_mfma_f32_16x16x32_bf16 v[42:45], v[10:13], v[34:37], 0
	s_waitcnt lgkmcnt(1)
	v_mfma_f32_16x16x32_bf16 v[38:41], v[2:5], v[34:37], 0
	s_waitcnt lgkmcnt(0)
	v_mfma_f32_16x16x32_bf16 v[34:37], v[6:9], v[34:37], 0
	s_cbranch_vccnz .LBB0_721
	ds_read_b128 v[176:179], v148 offset:10240
	ds_read_b128 v[180:183], v149 offset:14592
	ds_read_b128 v[184:187], v150 offset:18944
	ds_read_b128 v[188:191], v151 offset:23296
	ds_read_b128 v[192:195], v152 offset:27648
	ds_read_b128 v[196:199], v153 offset:32000
	ds_read_b128 v[220:223], v154 offset:36352
	ds_read_b128 v[240:243], v155 offset:40704
	s_waitcnt lgkmcnt(7)
	v_mfma_f32_16x16x32_bf16 v[62:65], v[176:179], v[74:77], v[62:65]
	s_waitcnt lgkmcnt(6)
	v_mfma_f32_16x16x32_bf16 v[58:61], v[180:183], v[74:77], v[58:61]
	s_waitcnt lgkmcnt(5)
	v_mfma_f32_16x16x32_bf16 v[54:57], v[184:187], v[74:77], v[54:57]
	s_waitcnt lgkmcnt(4)
	v_mfma_f32_16x16x32_bf16 v[50:53], v[188:191], v[74:77], v[50:53]
	s_waitcnt lgkmcnt(3)
	v_mfma_f32_16x16x32_bf16 v[46:49], v[192:195], v[74:77], v[46:49]
	s_waitcnt lgkmcnt(2)
	v_mfma_f32_16x16x32_bf16 v[42:45], v[196:199], v[74:77], v[42:45]
	s_waitcnt lgkmcnt(1)
	v_mfma_f32_16x16x32_bf16 v[38:41], v[220:223], v[74:77], v[38:41]
	s_waitcnt lgkmcnt(0)
	v_mfma_f32_16x16x32_bf16 v[34:37], v[240:243], v[74:77], v[34:37]
.LBB0_721:
	s_and_b64 vcc, exec, s[10:11]
	s_cbranch_vccnz .LBB0_723
	ds_read_b128 v[176:179], v156 offset:10240
	ds_read_b128 v[180:183], v157 offset:14592
	ds_read_b128 v[184:187], v158 offset:18944
	ds_read_b128 v[188:191], v159 offset:23296
	ds_read_b128 v[192:195], v160 offset:27648
	ds_read_b128 v[196:199], v161 offset:32000
	ds_read_b128 v[220:223], v162 offset:36352
	ds_read_b128 v[240:243], v163 offset:40704
	s_waitcnt lgkmcnt(7)
	v_mfma_f32_16x16x32_bf16 v[62:65], v[176:179], v[70:73], v[62:65]
	s_waitcnt lgkmcnt(6)
	v_mfma_f32_16x16x32_bf16 v[58:61], v[180:183], v[70:73], v[58:61]
	s_waitcnt lgkmcnt(5)
	v_mfma_f32_16x16x32_bf16 v[54:57], v[184:187], v[70:73], v[54:57]
	s_waitcnt lgkmcnt(4)
	v_mfma_f32_16x16x32_bf16 v[50:53], v[188:191], v[70:73], v[50:53]
	s_waitcnt lgkmcnt(3)
	v_mfma_f32_16x16x32_bf16 v[46:49], v[192:195], v[70:73], v[46:49]
	s_waitcnt lgkmcnt(2)
	v_mfma_f32_16x16x32_bf16 v[42:45], v[196:199], v[70:73], v[42:45]
	s_waitcnt lgkmcnt(1)
	v_mfma_f32_16x16x32_bf16 v[38:41], v[220:223], v[70:73], v[38:41]
	s_waitcnt lgkmcnt(0)
	v_mfma_f32_16x16x32_bf16 v[34:37], v[240:243], v[70:73], v[34:37]
.LBB0_723:
	s_and_b64 vcc, exec, s[6:7]
	s_cbranch_vccnz .LBB0_725
	ds_read_b128 v[176:179], v164 offset:10240
	ds_read_b128 v[180:183], v165 offset:14592
	ds_read_b128 v[184:187], v166 offset:18944
	ds_read_b128 v[188:191], v167 offset:23296
	ds_read_b128 v[192:195], v168 offset:27648
	ds_read_b128 v[196:199], v169 offset:32000
	ds_read_b128 v[220:223], v170 offset:36352
	ds_read_b128 v[240:243], v171 offset:40704
	s_waitcnt lgkmcnt(7)
	v_mfma_f32_16x16x32_bf16 v[62:65], v[176:179], v[66:69], v[62:65]
	s_waitcnt lgkmcnt(6)
	v_mfma_f32_16x16x32_bf16 v[58:61], v[180:183], v[66:69], v[58:61]
	s_waitcnt lgkmcnt(5)
	v_mfma_f32_16x16x32_bf16 v[54:57], v[184:187], v[66:69], v[54:57]
	s_waitcnt lgkmcnt(4)
	v_mfma_f32_16x16x32_bf16 v[50:53], v[188:191], v[66:69], v[50:53]
	s_waitcnt lgkmcnt(3)
	v_mfma_f32_16x16x32_bf16 v[46:49], v[192:195], v[66:69], v[46:49]
	s_waitcnt lgkmcnt(2)
	v_mfma_f32_16x16x32_bf16 v[42:45], v[196:199], v[66:69], v[42:45]
	s_waitcnt lgkmcnt(1)
	v_mfma_f32_16x16x32_bf16 v[38:41], v[220:223], v[66:69], v[38:41]
	s_waitcnt lgkmcnt(0)
	v_mfma_f32_16x16x32_bf16 v[34:37], v[240:243], v[66:69], v[34:37]

; __device__ __forceinline__ void cs_pair(int cu, int su0, int su1, const bf16* KVB, const bf16* w1k, const bf16* w1v, const bf16* w2k, const bf16* w2v, const float* bias1, const float* kn0, bf16* KCN, bf16* VCT, ...
;     ...
; #pragma unroll
;                 for (int ks = 0; ks < 4; ++ks) if (ks < nks) {
; #pragma unroll
;                     for (int dt = 0; dt < 8; ++dt) { const bf16x8 av = *(const bf16x8*)(vnT + (dt * 16 + qi) * 136 + (((ks * 4 + q4) ^ (dt * 2 + (qi >> 3))) << 3)); acc[dt] = __builtin_amdgcn_mfma_f32_16x16x32_bf16(av, bw[ks], acc[dt], 0, 0, 0); }
;                 }
.LBB0_735:
	ds_read_b128 v[176:179], v164 offset:10240
	ds_read_b128 v[180:183], v165 offset:14592
	ds_read_b128 v[184:187], v166 offset:18944
	ds_read_b128 v[188:191], v167 offset:23296
	ds_read_b128 v[192:195], v168 offset:27648
	ds_read_b128 v[196:199], v169 offset:32000
	ds_read_b128 v[220:223], v170 offset:36352
	ds_read_b128 v[240:243], v171 offset:40704
	s_waitcnt lgkmcnt(7)
	v_mfma_f32_16x16x32_bf16 v[42:45], v[176:179], v[34:37], v[42:45]
	s_waitcnt lgkmcnt(6)
	v_mfma_f32_16x16x32_bf16 v[38:41], v[180:183], v[34:37], v[38:41]
	s_waitcnt lgkmcnt(5)
	v_mfma_f32_16x16x32_bf16 v[26:29], v[184:187], v[34:37], v[26:29]
	s_waitcnt lgkmcnt(4)
	v_mfma_f32_16x16x32_bf16 v[22:25], v[188:191], v[34:37], v[22:25]
	s_waitcnt lgkmcnt(3)
	v_mfma_f32_16x16x32_bf16 v[18:21], v[192:195], v[34:37], v[18:21]
	s_waitcnt lgkmcnt(2)
	v_mfma_f32_16x16x32_bf16 v[14:17], v[196:199], v[34:37], v[14:17]
	s_waitcnt lgkmcnt(1)
	v_mfma_f32_16x16x32_bf16 v[10:13], v[220:223], v[34:37], v[10:13]
	s_waitcnt lgkmcnt(0)
	v_mfma_f32_16x16x32_bf16 v[2:5], v[240:243], v[34:37], v[2:5]

; __device__ __forceinline__ void cs_pair(int cu, int su0, int su1, const bf16* KVB, const bf16* w1k, const bf16* w1v, const bf16* w2k, const bf16* w2v, const float* bias1, const float* kn0, bf16* KCN, bf16* VCT, ...
;     ...
; #pragma unroll
;                 for (int ks = 0; ks < 4; ++ks) if (ks < nks) {
; #pragma unroll
;                     for (int dt = 0; dt < 8; ++dt) { const bf16x8 av = *(const bf16x8*)(vnT + (dt * 16 + qi) * 136 + (((ks * 4 + q4) ^ (dt * 2 + (qi >> 3))) << 3)); acc[dt] = __builtin_amdgcn_mfma_f32_16x16x32_bf16(av, bw[ks], acc[dt], 0, 0, 0); }
;                 }
.LBB0_743:
	ds_read_b128 v[176:179], v148 offset:10240
	ds_read_b128 v[180:183], v149 offset:14592
	ds_read_b128 v[184:187], v150 offset:18944
	ds_read_b128 v[188:191], v151 offset:23296
	ds_read_b128 v[192:195], v152 offset:27648
	ds_read_b128 v[196:199], v153 offset:32000
	ds_read_b128 v[220:223], v154 offset:36352
	ds_read_b128 v[240:243], v155 offset:40704
	s_waitcnt lgkmcnt(7)
	v_mfma_f32_16x16x32_bf16 v[42:45], v[176:179], v[50:53], v[42:45]
	s_waitcnt lgkmcnt(6)
	v_mfma_f32_16x16x32_bf16 v[38:41], v[180:183], v[50:53], v[38:41]
	s_waitcnt lgkmcnt(5)
	v_mfma_f32_16x16x32_bf16 v[26:29], v[184:187], v[50:53], v[26:29]
	s_waitcnt lgkmcnt(4)
	v_mfma_f32_16x16x32_bf16 v[22:25], v[188:191], v[50:53], v[22:25]
	s_waitcnt lgkmcnt(3)
	v_mfma_f32_16x16x32_bf16 v[18:21], v[192:195], v[50:53], v[18:21]
	s_waitcnt lgkmcnt(2)
	v_mfma_f32_16x16x32_bf16 v[14:17], v[196:199], v[50:53], v[14:17]
	s_waitcnt lgkmcnt(1)
	v_mfma_f32_16x16x32_bf16 v[10:13], v[220:223], v[50:53], v[10:13]
	s_waitcnt lgkmcnt(0)
	v_mfma_f32_16x16x32_bf16 v[2:5], v[240:243], v[50:53], v[2:5]
	s_and_b64 vcc, exec, s[10:11]
	s_cbranch_vccnz .LBB0_734
.LBB0_744:
	ds_read_b128 v[176:179], v156 offset:10240
	ds_read_b128 v[180:183], v157 offset:14592
	ds_read_b128 v[184:187], v158 offset:18944
	ds_read_b128 v[188:191], v159 offset:23296
	ds_read_b128 v[192:195], v160 offset:27648
	ds_read_b128 v[196:199], v161 offset:32000
	ds_read_b128 v[220:223], v162 offset:36352
	ds_read_b128 v[240:243], v163 offset:40704
	s_waitcnt lgkmcnt(7)
	v_mfma_f32_16x16x32_bf16 v[42:45], v[176:179], v[46:49], v[42:45]
	s_waitcnt lgkmcnt(6)
	v_mfma_f32_16x16x32_bf16 v[38:41], v[180:183], v[46:49], v[38:41]
	s_waitcnt lgkmcnt(5)
	v_mfma_f32_16x16x32_bf16 v[26:29], v[184:187], v[46:49], v[26:29]
	s_waitcnt lgkmcnt(4)
	v_mfma_f32_16x16x32_bf16 v[22:25], v[188:191], v[46:49], v[22:25]
	s_waitcnt lgkmcnt(3)
	v_mfma_f32_16x16x32_bf16 v[18:21], v[192:195], v[46:49], v[18:21]
	s_waitcnt lgkmcnt(2)
	v_mfma_f32_16x16x32_bf16 v[14:17], v[196:199], v[46:49], v[14:17]
	s_waitcnt lgkmcnt(1)
	v_mfma_f32_16x16x32_bf16 v[10:13], v[220:223], v[46:49], v[10:13]
	s_waitcnt lgkmcnt(0)
	v_mfma_f32_16x16x32_bf16 v[2:5], v[240:243], v[46:49], v[2:5]
	s_and_b64 vcc, exec, s[6:7]
	s_cbranch_vccz .LBB0_735
	s_branch .LBB0_736
